# w_out sample rows: the partial-slab sum moved to 128 otherwise early workgroups ahead of their main tile (write-through + arrival count), workgroups 0..63 only wait for it
# speedup vs baseline: 1.0377x; 1.0309x over previous
; DI void mixers_phase(ArgsP a, LAS unsigned char* lds, int l, int tid) {
;     ...
;     const int wave = tid >> 6, lane = tid & 63, gw = blockIdx.x * 8 + wave, NGW = gridDim.x * 8;
;     const int vcb = (gridDim.x % 8 == 0) ? (blockIdx.x % 8) * (gridDim.x / 8) + blockIdx.x / 8 : blockIdx.x;
;     for (int rp = 0; rp < 1 + ((MIXM >> 0) & 1); ++rp) for (int u = vcb; u < 256; u += gridDim.x) attn_prompt_unit(lds, u, Q, KB, VB, YB, a->in[16] + l * 8, tid);
;     for (int rp = 0; rp < 1 + ((MIXM >> 1) & 1); ++rp) for (int t = vcb; t < 256; t += gridDim.x) s5_prompt_task(lds, t, l, a, U, YC0, tid);
;     for (int rp = 0; rp < 1 + ((MIXM >> 2) & 1); ++rp) for (int t = gw; t < 4096; t += NGW) s5_sample_task(lds, t, l, a, U, YC0, tid);
;     __syncthreads();
;     for (int rp = 0; rp < 1 + ((MIXM >> 3) & 1); ++rp) for (int t = gw; t < 1024; t += NGW) attn_sample_task(lds + wave * 4096, t, l, a, Q, YB, lane);
; }
; __global__ void __launch_bounds__(512, 2) mega(Args a_unused) {
;     ...
;         if (ph + 1 < ph_hi) { if (SYNC2 == 1 || ph_hi > 1000) grid.sync(); else { XcdBarrier xb = xbar; asm volatile("" : "+s"(xb.x), "+s"(xb.bar));
;             xcd_barrier(xb); if (SYNC2 == 2) xcd_barrier(xb); } }
.LBB0_6:
	s_and_b32 s2, s76, 7
	s_lshr_b32 s3, s82, 3
	s_mul_i32 s2, s3, s2
	s_lshr_b32 s3, s76, 3
	s_and_b32 s90, s4, 0xffffffc0
	s_mul_i32 s0, s83, s82
	s_lshl_b32 s83, s76, 3
	s_lshl_b32 s48, s82, 3
	s_lshl_b32 s91, s76, 9
	s_lshl_b32 s50, s82, 9
	s_and_b32 s1, s82, 7
	s_load_dword s5, s[78:79], 0x168
	s_add_i32 s2, s2, s3
	s_cmpk_lt_i32 s87, 0x3e9
	s_cselect_b64 s[6:7], -1, 0
	s_cmp_eq_u32 s1, 0
	s_cselect_b32 s95, s2, s76
	v_writelane_b32 v254, s6, 4
	s_cmpk_lt_i32 s95, 0x100
	s_waitcnt lgkmcnt(0)
	s_mul_i32 s92, s0, s5
	v_writelane_b32 v254, s7, 5
	s_cselect_b64 s[0:1], -1, 0
	v_writelane_b32 v254, s0, 6
	v_lshrrev_b32_e32 v2, 20, v0
	v_lshrrev_b32_e32 v0, 10, v0
	v_writelane_b32 v254, s1, 7
	s_lshl_b32 s0, s76, 10
	v_writelane_b32 v254, s0, 8
	s_lshl_b32 s0, s4, 2
	s_and_b32 s0, s0, 0xffffff00
	v_writelane_b32 v254, s0, 9
	s_add_i32 s0, s90, 0x24d40
	v_writelane_b32 v254, s0, 10
	s_flbit_i32_b32 s0, 0
	s_min_u32 s65, s0, 32
	s_add_i32 s0, 0, 0x9000
	v_writelane_b32 v254, s0, 11
	s_add_i32 s0, 0, 0x11000
	v_writelane_b32 v254, s0, 12
	s_add_i32 s0, 0, 0x11180
	v_or_b32_e32 v0, v0, v2
	s_movk_i32 s93, 0x3ff
	v_writelane_b32 v254, s0, 13
	s_add_i32 s0, 0, 0x21000
	v_and_or_b32 v0, v0, s93, v1
	v_writelane_b32 v254, s0, 14
	s_add_i32 s0, 0, 0x21004
	v_writelane_b32 v254, s0, 15
	v_cmp_eq_u32_e64 s[0:1], 0, v0
	s_ashr_i32 s51, s50, 31
	s_lshl_b32 s84, s82, 10
	v_writelane_b32 v254, s0, 16
	v_mbcnt_lo_u32_b32 v1, -1, 0
	s_ashr_i32 s49, s48, 31
	v_writelane_b32 v254, s1, 17
	s_lshl_b64 s[0:1], s[50:51], 1
	v_writelane_b32 v254, s0, 18
	v_mov_b32_e32 v97, 0
	s_movk_i32 s96, 0x200
	v_writelane_b32 v254, s1, 19
	s_lshl_b64 s[0:1], s[50:51], 4
	v_writelane_b32 v254, s0, 20
	s_mov_b32 s97, 0x200000
	s_mov_b32 s75, 0x400000
	v_writelane_b32 v254, s1, 21
	s_mov_b32 s74, 0x600000
	s_mov_b32 s42, 0x800000
	s_mov_b32 s72, 0xa00000
	s_mov_b32 s73, 0xc00000
	s_mov_b32 s46, 0xe00000
	s_mov_b32 s60, 0x1000000
	s_mov_b32 s70, 0x1200000
	s_mov_b32 s71, 0x1400000
	s_movk_i32 s61, 0x1800
	s_movk_i32 s64, 0x1600
	v_mov_b32_e32 v195, 0xff800000
	v_mbcnt_hi_u32_b32 v196, -1, v1
	v_mov_b32_e32 v197, 0x7f800000
	s_movk_i32 s66, 0x84
	s_mov_b32 s67, 0xff800000
	s_movk_i32 s94, 0x7fff
	s_movk_i32 s47, 0x1300
	s_mov_b32 s57, 0
	s_lshl_b64 s[58:59], s[50:51], 2
	s_lshl_b64 s[62:63], s[50:51], 6
	s_mov_b64 s[68:69], 0x80
	v_writelane_b32 v254, s84, 22
	s_mov_b32 s100, 0
	s_branch .LBB0_11

; __device__ __forceinline__ int lane_id_v() { int l; asm volatile("v_mbcnt_lo_u32_b32 %0, -1, 0\n\tv_mbcnt_hi_u32_b32 %0, -1, %0" : "=v"(l)); return l; }
; __device__ __forceinline__ void st_bf4(bf16_t* p, const f32x4 v) { u32x2 w; w.x = cvt_pk_bf16(v[0], v[1]); w.y = cvt_pk_bf16(v[2], v[3]); *(u32x2*)p = w; }
; __global__ void __launch_bounds__(512, 2) mega(Args a_unused) {
;     ...
;                 { pg8::Gemm g{H, (const bf16_t*)(ws + WS_WOUT) + (size_t)l * 1024 * 1024, MP, 1024, 1024, 0, 0}; pg8::StaticOrder S; S.init(MP, 1024, G, c);
;                   pg8::EpiRes E{xp, rep ? (float*)(ws + WS_XA) : X, MOD + l * 6144 + 2048};
;                   pg8::gemm_phase<pg8::EpiRes, pg8::StaticOrder, true, true>(lds, g, S, E, wave_s * 64 + lane_id_v()); }
;                 for (int j = c; j < 64; j += G) { const int ks = j & 7, pmr = j >> 5; const float* Pm = (const float*)(ws + WS_Q);
;                     for (int e2 = wave_s * 64 + lane_id_v(); e2 < 256 * 32; e2 += 512) { const int rs = pmr * 256 + (e2 >> 5), c4 = ks * 128 + (e2 & 31) * 4; f32x4 s = {0.f, 0.f, 0.f, 0.f};
; #pragma unroll
;                         for (int p = 0; p < 12; ++p) s += *(const f32x4*)(Pm + ((size_t)p * 512 + rs) * 1024 + c4);
;                         st_bf4(H + (size_t)(MP + rs) * 1024 + c4, s); } }
.LBB0_231:
	s_cmp_gt_i32 s86, 4
	s_mov_b64 s[2:3], -1
	s_cbranch_scc0 .LBB0_281
	s_cmpk_lg_i32 s51, 0x100
	s_cbranch_scc1 .Lwp_skip
	s_addk_i32 s100, 0x80
	s_sub_i32 s101, s38, 64
	s_cmp_gt_u32 s101, 0x7f
	s_cbranch_scc1 .Lwp_skip
	s_lshr_b32 s6, s101, 6
	s_lshl_b32 s6, s6, 8
	s_and_b32 s10, s101, 7
	s_lshl_b32 s10, s10, 5
	s_add_i32 s6, s6, s10
	s_lshr_b32 s10, s101, 3
	s_and_b32 s10, s10, 7
	s_lshl_b32 s10, s10, 7
	s_add_u32 s8, s26, 0xf200000
	s_addc_u32 s9, s27, 0
	v_lshrrev_b32_e32 v142, 5, v194
	v_add_u32_e32 v142, s6, v142
	v_and_b32_e32 v143, 31, v194
	v_lshl_add_u32 v143, v143, 2, s10
	v_lshlrev_b32_e32 v144, 12, v142
	v_lshl_add_u32 v144, v143, 2, v144
	v_add_u32_e32 v168, 0x10000, v144
	global_load_dwordx4 v[198:201], v144, s[8:9]
	v_add_u32_e32 v145, 0x200000, v144
	global_load_dwordx4 v[202:205], v145, s[8:9]
	v_add_u32_e32 v166, 0x400000, v144
	global_load_dwordx4 v[206:209], v166, s[8:9]
	v_add_u32_e32 v145, 0x600000, v144
	global_load_dwordx4 v[210:213], v145, s[8:9]
	v_add_u32_e32 v166, 0x800000, v144
	global_load_dwordx4 v[214:217], v166, s[8:9]
	v_add_u32_e32 v145, 0xa00000, v144
	global_load_dwordx4 v[218:221], v145, s[8:9]
	v_add_u32_e32 v166, 0xc00000, v144
	global_load_dwordx4 v[222:225], v166, s[8:9]
	v_add_u32_e32 v145, 0xe00000, v144
	global_load_dwordx4 v[226:229], v145, s[8:9]
	v_add_u32_e32 v166, 0x1000000, v144
	global_load_dwordx4 v[230:233], v166, s[8:9]
	v_add_u32_e32 v145, 0x1200000, v144
	global_load_dwordx4 v[234:237], v145, s[8:9]
	v_add_u32_e32 v166, 0x1400000, v144
	global_load_dwordx4 v[238:241], v166, s[8:9]
	v_add_u32_e32 v145, 0x1600000, v144
	global_load_dwordx4 v[242:245], v145, s[8:9]
	global_load_dwordx4 v[148:151], v168, s[8:9]
	v_add_u32_e32 v145, 0x200000, v168
	global_load_dwordx4 v[152:155], v145, s[8:9]
	v_add_u32_e32 v166, 0x400000, v168
	global_load_dwordx4 v[156:159], v166, s[8:9]
	v_add_u32_e32 v145, 0x600000, v168
	global_load_dwordx4 v[160:163], v145, s[8:9]
	v_add_u32_e32 v166, 0x800000, v168
	global_load_dwordx4 v[170:173], v166, s[8:9]
	v_add_u32_e32 v145, 0xa00000, v168
	global_load_dwordx4 v[174:177], v145, s[8:9]
	v_add_u32_e32 v166, 0xc00000, v168
	global_load_dwordx4 v[182:185], v166, s[8:9]
	v_add_u32_e32 v145, 0xe00000, v168
	global_load_dwordx4 v[186:189], v145, s[8:9]
	v_add_u32_e32 v166, 0x1000000, v168
	global_load_dwordx4 v[190:193], v166, s[8:9]
	v_add_u32_e32 v145, 0x1200000, v168
	global_load_dwordx4 v[124:127], v145, s[8:9]
	v_add_u32_e32 v166, 0x1400000, v168
	global_load_dwordx4 v[128:131], v166, s[8:9]
	v_add_u32_e32 v145, 0x1600000, v168
	global_load_dwordx4 v[138:141], v145, s[8:9]
	v_lshlrev_b32_e32 v164, 11, v142
	v_lshl_add_u32 v164, v143, 1, v164
	v_add_u32_e32 v164, 0x2000000, v164
	s_waitcnt vmcnt(12)
	v_pk_add_f32 v[246:247], v[198:199], 0 op_sel_hi:[1,0]
	v_pk_add_f32 v[248:249], v[200:201], 0 op_sel_hi:[1,0]
	v_pk_add_f32 v[246:247], v[246:247], v[202:203]
	v_pk_add_f32 v[248:249], v[248:249], v[204:205]
	v_pk_add_f32 v[246:247], v[246:247], v[206:207]
	v_pk_add_f32 v[248:249], v[248:249], v[208:209]
	v_pk_add_f32 v[246:247], v[246:247], v[210:211]
	v_pk_add_f32 v[248:249], v[248:249], v[212:213]
	v_pk_add_f32 v[246:247], v[246:247], v[214:215]
	v_pk_add_f32 v[248:249], v[248:249], v[216:217]
	v_pk_add_f32 v[246:247], v[246:247], v[218:219]
	v_pk_add_f32 v[248:249], v[248:249], v[220:221]
	v_pk_add_f32 v[246:247], v[246:247], v[222:223]
	v_pk_add_f32 v[248:249], v[248:249], v[224:225]
	v_pk_add_f32 v[246:247], v[246:247], v[226:227]
	v_pk_add_f32 v[248:249], v[248:249], v[228:229]
	v_pk_add_f32 v[246:247], v[246:247], v[230:231]
	v_pk_add_f32 v[248:249], v[248:249], v[232:233]
	v_pk_add_f32 v[246:247], v[246:247], v[234:235]
	v_pk_add_f32 v[248:249], v[248:249], v[236:237]
	v_pk_add_f32 v[246:247], v[246:247], v[238:239]
	v_pk_add_f32 v[248:249], v[248:249], v[240:241]
	v_pk_add_f32 v[246:247], v[246:247], v[242:243]
	v_pk_add_f32 v[248:249], v[248:249], v[244:245]
	v_cvt_pk_bf16_f32 v246, v246, v247
	v_cvt_pk_bf16_f32 v247, v248, v249
	global_store_dwordx2 v164, v[246:247], s[88:89] sc1
	v_add_u32_e32 v165, 0x8000, v164
	s_waitcnt vmcnt(1)
	v_pk_add_f32 v[250:251], v[148:149], 0 op_sel_hi:[1,0]
	v_pk_add_f32 v[252:253], v[150:151], 0 op_sel_hi:[1,0]
	v_pk_add_f32 v[250:251], v[250:251], v[152:153]
	v_pk_add_f32 v[252:253], v[252:253], v[154:155]
	v_pk_add_f32 v[250:251], v[250:251], v[156:157]
	v_pk_add_f32 v[252:253], v[252:253], v[158:159]
	v_pk_add_f32 v[250:251], v[250:251], v[160:161]
	v_pk_add_f32 v[252:253], v[252:253], v[162:163]
	v_pk_add_f32 v[250:251], v[250:251], v[170:171]
	v_pk_add_f32 v[252:253], v[252:253], v[172:173]
	v_pk_add_f32 v[250:251], v[250:251], v[174:175]
	v_pk_add_f32 v[252:253], v[252:253], v[176:177]
	v_pk_add_f32 v[250:251], v[250:251], v[182:183]
	v_pk_add_f32 v[252:253], v[252:253], v[184:185]
	v_pk_add_f32 v[250:251], v[250:251], v[186:187]
	v_pk_add_f32 v[252:253], v[252:253], v[188:189]
	v_pk_add_f32 v[250:251], v[250:251], v[190:191]
	v_pk_add_f32 v[252:253], v[252:253], v[192:193]
	v_pk_add_f32 v[250:251], v[250:251], v[124:125]
	v_pk_add_f32 v[252:253], v[252:253], v[126:127]
	v_pk_add_f32 v[250:251], v[250:251], v[128:129]
	v_pk_add_f32 v[252:253], v[252:253], v[130:131]
	v_pk_add_f32 v[250:251], v[250:251], v[138:139]
	v_pk_add_f32 v[252:253], v[252:253], v[140:141]
	v_cvt_pk_bf16_f32 v250, v250, v251
	v_cvt_pk_bf16_f32 v251, v252, v253
	global_store_dwordx2 v165, v[250:251], s[88:89] sc1
	s_waitcnt vmcnt(0)
	s_barrier
	v_cmp_eq_u32_e64 s[10:11], 0, v194
	s_and_saveexec_b64 s[22:23], s[10:11]
	v_mov_b32_e32 v144, 0x3c00
	v_mov_b32_e32 v145, 0
	v_lshl_add_u64 v[142:143], s[26:27], 0, v[144:145]
	v_mov_b32_e32 v148, 1
	flat_atomic_add v[142:143], v148
	s_or_b64 exec, exec, s[22:23]
.Lwp_skip:
	v_readlane_b32 s2, v254, 31
	v_readlane_b32 s3, v254, 32
	s_lshl_b64 s[2:3], s[2:3], 21
	s_add_u32 s2, s26, s2
	s_addc_u32 s3, s27, s3
	s_add_u32 s28, s2, 0x3500000
	s_addc_u32 s29, s3, 0
	v_mbcnt_lo_u32_b32 v0, -1, 0
	v_mbcnt_hi_u32_b32 v0, -1, v0
	s_cmpk_gt_i32 s38, 0xff
	v_add_u32_e32 v8, s90, v0
	s_nop 0
	v_readfirstlane_b32 s5, v8
	s_cbranch_scc1 .LBB0_256
	s_ashr_i32 s30, s38, 31
	s_lshr_b32 s2, s30, 29
	s_add_i32 s6, s38, s2
	s_and_b32 s2, s6, -8
	s_sub_i32 s7, s38, s2
	s_cmp_gt_i32 s7, -1
	s_mov_b64 s[2:3], -1
	s_cbranch_scc0 .LBB0_235
	s_lshl_b32 s4, s7, 5
	s_mov_b64 s[2:3], 0

; __device__ __forceinline__ int lane_id_v() { int l; asm volatile("v_mbcnt_lo_u32_b32 %0, -1, 0\n\tv_mbcnt_hi_u32_b32 %0, -1, %0" : "=v"(l)); return l; }
; __device__ __forceinline__ void st_bf4(bf16_t* p, const f32x4 v) { u32x2 w; w.x = cvt_pk_bf16(v[0], v[1]); w.y = cvt_pk_bf16(v[2], v[3]); *(u32x2*)p = w; }
; __global__ void __launch_bounds__(512, 2) mega(Args a_unused) {
;     ...
;                 for (int j = c; j < 64; j += G) { const int ks = j & 7, pmr = j >> 5; const float* Pm = (const float*)(ws + WS_Q);
;                     for (int e2 = wave_s * 64 + lane_id_v(); e2 < 256 * 32; e2 += 512) { const int rs = pmr * 256 + (e2 >> 5), c4 = ks * 128 + (e2 & 31) * 4; f32x4 s = {0.f, 0.f, 0.f, 0.f};
; #pragma unroll
;                         for (int p = 0; p < 12; ++p) s += *(const f32x4*)(Pm + ((size_t)p * 512 + rs) * 1024 + c4);
;                         st_bf4(H + (size_t)(MP + rs) * 1024 + c4, s); } }
;                 asm volatile("s_waitcnt vmcnt(0)" ::: "memory"); __syncthreads();
.LBB0_256:
	s_cmp_lt_i32 s38, 64
	s_cselect_b64 s[2:3], -1, 0
	s_cmp_gt_i32 s38, 63
	s_cbranch_scc1 .LBB0_262
	s_cmpk_lg_i32 s51, 0x100
	s_cbranch_scc1 .Lwc_orig
	v_cmp_eq_u32_e64 s[6:7], 0, v194
	s_and_saveexec_b64 s[8:9], s[6:7]
	s_cbranch_execz .Lwc_done
	v_mov_b32_e32 v2, 0x3c00
	v_mov_b32_e32 v3, 0
	v_lshl_add_u64 v[2:3], s[26:27], 0, v[2:3]
.Lwc_poll:
	flat_load_dword v0, v[2:3] sc1
	s_waitcnt vmcnt(0) lgkmcnt(0)
	v_cmp_le_u32_e64 s[10:11], s100, v0
	s_and_b64 vcc, exec, s[10:11]
	s_cbranch_vccnz .Lwc_got
	s_sleep 2
	s_branch .Lwc_poll
.Lwc_got:
	buffer_inv sc1
	s_waitcnt vmcnt(0)
.Lwc_done:
	s_or_b64 exec, exec, s[8:9]
	s_branch .LBB0_262
.Lwc_orig:
	s_add_u32 s4, s26, 0xf200000
	s_addc_u32 s5, s27, 0
	s_mov_b32 s10, s38
	s_branch .LBB0_259

; __global__ void __launch_bounds__(512, 2) mega(Args a_unused) {
	.amdhsa_kernel _Z4mega4Args
		.amdhsa_group_segment_fixed_size 0
		.amdhsa_private_segment_fixed_size 0
		.amdhsa_kernarg_size 608
		.amdhsa_user_sgpr_count 2
		.amdhsa_user_sgpr_dispatch_ptr 0
		.amdhsa_user_sgpr_queue_ptr 0
		.amdhsa_user_sgpr_kernarg_segment_ptr 1
		.amdhsa_user_sgpr_dispatch_id 0
		.amdhsa_user_sgpr_kernarg_preload_length 0
		.amdhsa_user_sgpr_kernarg_preload_offset 0
		.amdhsa_user_sgpr_private_segment_size 0
		.amdhsa_uses_dynamic_stack 0
		.amdhsa_enable_private_segment 0
		.amdhsa_system_sgpr_workgroup_id_x 1
		.amdhsa_system_sgpr_workgroup_id_y 0
		.amdhsa_system_sgpr_workgroup_id_z 0
		.amdhsa_system_sgpr_workgroup_info 0
		.amdhsa_system_vgpr_workitem_id 2
		.amdhsa_next_free_vgpr 256
		.amdhsa_next_free_sgpr 102
		.amdhsa_accum_offset 256
		.amdhsa_reserve_vcc 1
		.amdhsa_float_round_mode_32 0
		.amdhsa_float_round_mode_16_64 0
		.amdhsa_float_denorm_mode_32 3
		.amdhsa_float_denorm_mode_16_64 3
		.amdhsa_dx10_clamp 1
		.amdhsa_ieee_mode 1
		.amdhsa_fp16_overflow 0
		.amdhsa_tg_split 0
		.amdhsa_exception_fp_ieee_invalid_op 0
		.amdhsa_exception_fp_denorm_src 0
		.amdhsa_exception_fp_ieee_div_zero 0
		.amdhsa_exception_fp_ieee_overflow 0
		.amdhsa_exception_fp_ieee_underflow 0
		.amdhsa_exception_fp_ieee_inexact 0
		.amdhsa_exception_int_div_zero 0
	.end_amdhsa_kernel

; __global__ void __launch_bounds__(512, 2) mega(Args a_unused) {
amdhsa.kernels:
  - .agpr_count:     0
    .args:
      - .offset:         0
        .size:           352
        .value_kind:     by_value
      - .offset:         352
        .size:           4
        .value_kind:     hidden_block_count_x
      - .offset:         356
        .size:           4
        .value_kind:     hidden_block_count_y
      - .offset:         360
        .size:           4
        .value_kind:     hidden_block_count_z
      - .offset:         364
        .size:           2
        .value_kind:     hidden_group_size_x
      - .offset:         366
        .size:           2
        .value_kind:     hidden_group_size_y
      - .offset:         368
        .size:           2
        .value_kind:     hidden_group_size_z
      - .offset:         370
        .size:           2
        .value_kind:     hidden_remainder_x
      - .offset:         372
        .size:           2
        .value_kind:     hidden_remainder_y
      - .offset:         374
        .size:           2
        .value_kind:     hidden_remainder_z
      - .offset:         392
        .size:           8
        .value_kind:     hidden_global_offset_x
      - .offset:         400
        .size:           8
        .value_kind:     hidden_global_offset_y
      - .offset:         408
        .size:           8
        .value_kind:     hidden_global_offset_z
      - .offset:         416
        .size:           2
        .value_kind:     hidden_grid_dims
      - .offset:         440
        .size:           8
        .value_kind:     hidden_multigrid_sync_arg
      - .offset:         472
        .size:           4
        .value_kind:     hidden_dynamic_lds_size
    .group_segment_fixed_size: 0
    .kernarg_segment_align: 8
    .kernarg_segment_size: 608
    .language:       OpenCL C
    .language_version:
      - 2
      - 0
    .max_flat_workgroup_size: 512
    .name:           _Z4mega4Args
    .private_segment_fixed_size: 0
    .sgpr_count:     108
    .sgpr_spill_count: 75
    .symbol:         _Z4mega4Args.kd
    .uniform_work_group_size: 1
    .uses_dynamic_stack: false
    .vgpr_count:     256
    .vgpr_spill_count: 0
    .wavefront_size: 64
